# K-loop LDS-DMA loads use the scalar-base + 32-bit VGPR offset form: 8 v_lshl_add_u64 address ops per K-tile per wave removed
# speedup vs baseline: 1.0041x; 1.0008x over previous
.LBB0_169:
	s_add_u32 s34, s50, 0xfff80080
	s_addc_u32 s35, s51, -1
	s_add_i32 s52, 0, 0x10000
	s_cmp_eq_u32 s77, 28
	s_cselect_b32 s55, s36, s35
	s_cselect_b32 s54, s37, s34
	v_add_u32_e32 v145, s52, v142
	s_cselect_b32 s35, s41, s76
	s_cselect_b32 s34, s43, s71
	s_add_i32 s53, 0, 0x14000
	ds_read_b128 v[146:149], v145
	ds_read_b128 v[150:153], v145 offset:1024
	ds_read_b128 v[172:175], v145 offset:2048
	ds_read_b128 v[176:179], v145 offset:3072
	v_add_u32_e32 v145, s53, v142
	ds_read_b128 v[180:183], v145
	ds_read_b128 v[184:187], v145 offset:1024
	ds_read_b128 v[188:191], v145 offset:2048
	ds_read_b128 v[192:195], v145 offset:3072
	s_add_i32 m0, s57, 0xc000
	ds_read_b128 v[196:199], v144
	ds_read_b128 v[200:203], v144 offset:1024
	ds_read_b128 v[204:207], v144 offset:2048
	ds_read_b128 v[208:211], v144 offset:3072
	ds_read_b128 v[212:215], v144 offset:4096
	ds_read_b128 v[216:219], v144 offset:5120
	ds_read_b128 v[228:231], v144 offset:6144
	ds_read_b128 v[232:235], v144 offset:7168
	global_load_lds_dwordx4 v138, s[50:51]
	s_add_i32 m0, s57, 0xe000
	s_nop 0
	global_load_lds_dwordx4 v140, s[50:51]
	s_waitcnt vmcnt(8)
	s_waitcnt lgkmcnt(0)
	s_barrier
	s_setprio 1
	v_mfma_f32_16x16x32_bf16 v[128:131], v[146:149], v[196:199], v[128:131]
	v_mfma_f32_16x16x32_bf16 v[128:131], v[150:153], v[200:203], v[128:131]
	v_mfma_f32_16x16x32_bf16 v[124:127], v[172:175], v[196:199], v[124:127]
	v_mfma_f32_16x16x32_bf16 v[124:127], v[176:179], v[200:203], v[124:127]
	v_mfma_f32_16x16x32_bf16 v[108:111], v[172:175], v[204:207], v[108:111]
	v_mfma_f32_16x16x32_bf16 v[108:111], v[176:179], v[208:211], v[108:111]
	v_mfma_f32_16x16x32_bf16 v[112:115], v[146:149], v[204:207], v[112:115]
	v_mfma_f32_16x16x32_bf16 v[112:115], v[150:153], v[208:211], v[112:115]
	v_mfma_f32_16x16x32_bf16 v[96:99], v[146:149], v[212:215], v[96:99]
	v_mfma_f32_16x16x32_bf16 v[96:99], v[150:153], v[216:219], v[96:99]
	v_mfma_f32_16x16x32_bf16 v[92:95], v[172:175], v[212:215], v[92:95]
	v_mfma_f32_16x16x32_bf16 v[92:95], v[176:179], v[216:219], v[92:95]
	v_mfma_f32_16x16x32_bf16 v[76:79], v[172:175], v[228:231], v[76:79]
	v_mfma_f32_16x16x32_bf16 v[76:79], v[176:179], v[232:235], v[76:79]
	v_mfma_f32_16x16x32_bf16 v[80:83], v[146:149], v[228:231], v[80:83]
	v_mfma_f32_16x16x32_bf16 v[80:83], v[150:153], v[232:235], v[80:83]
	v_mfma_f32_16x16x32_bf16 v[120:123], v[180:183], v[196:199], v[120:123]
	v_mfma_f32_16x16x32_bf16 v[120:123], v[184:187], v[200:203], v[120:123]
	v_mfma_f32_16x16x32_bf16 v[116:119], v[188:191], v[196:199], v[116:119]
	v_mfma_f32_16x16x32_bf16 v[116:119], v[192:195], v[200:203], v[116:119]
	v_mfma_f32_16x16x32_bf16 v[100:103], v[188:191], v[204:207], v[100:103]
	v_mfma_f32_16x16x32_bf16 v[100:103], v[192:195], v[208:211], v[100:103]
	v_mfma_f32_16x16x32_bf16 v[104:107], v[180:183], v[204:207], v[104:107]
	v_mfma_f32_16x16x32_bf16 v[104:107], v[184:187], v[208:211], v[104:107]
	v_mfma_f32_16x16x32_bf16 v[88:91], v[180:183], v[212:215], v[88:91]
	v_mfma_f32_16x16x32_bf16 v[88:91], v[184:187], v[216:219], v[88:91]
	v_mfma_f32_16x16x32_bf16 v[84:87], v[188:191], v[212:215], v[84:87]
	v_mfma_f32_16x16x32_bf16 v[84:87], v[192:195], v[216:219], v[84:87]
	v_mfma_f32_16x16x32_bf16 v[68:71], v[188:191], v[228:231], v[68:71]
	v_mfma_f32_16x16x32_bf16 v[68:71], v[192:195], v[232:235], v[68:71]
	v_mfma_f32_16x16x32_bf16 v[72:75], v[180:183], v[228:231], v[72:75]
	v_mfma_f32_16x16x32_bf16 v[72:75], v[184:187], v[232:235], v[72:75]
	s_setprio 0
	s_barrier
	s_add_u32 s100, s54, s14
	s_addc_u32 s101, s55, s15
	s_add_i32 s52, s52, s19
	s_mov_b32 m0, s52
	ds_read_b128 v[196:199], v144 offset:16384
	ds_read_b128 v[200:203], v144 offset:17408
	ds_read_b128 v[204:207], v144 offset:18432
	ds_read_b128 v[208:211], v144 offset:19456
	ds_read_b128 v[212:215], v144 offset:20480
	ds_read_b128 v[216:219], v144 offset:21504
	ds_read_b128 v[228:231], v144 offset:22528
	ds_read_b128 v[232:235], v144 offset:23552
	global_load_lds_dwordx4 v134, s[34:35]
	s_add_i32 m0, s52, 0x2000
	s_add_u32 s96, s34, 0x4000
	s_addc_u32 s97, s35, 0
	s_add_i32 s52, s53, s19
	global_load_lds_dwordx4 v0, s[34:35]
	s_mov_b32 m0, s52
	s_nop 0
	global_load_lds_dwordx4 v134, s[96:97]
	s_add_i32 m0, s52, 0x2000
	s_nop 0
	global_load_lds_dwordx4 v0, s[96:97]
	s_mov_b32 m0, s57
	s_nop 0
	global_load_lds_dwordx4 v136, s[54:55]
	s_mov_b32 m0, s58
	s_nop 0
	global_load_lds_dwordx4 v132, s[54:55]
	s_waitcnt vmcnt(8)
	s_waitcnt lgkmcnt(0)
	s_barrier
	s_setprio 1
	v_mfma_f32_16x16x32_bf16 v[64:67], v[146:149], v[196:199], v[64:67]
	v_mfma_f32_16x16x32_bf16 v[64:67], v[150:153], v[200:203], v[64:67]
	v_mfma_f32_16x16x32_bf16 v[60:63], v[172:175], v[196:199], v[60:63]
	v_mfma_f32_16x16x32_bf16 v[60:63], v[176:179], v[200:203], v[60:63]
	v_mfma_f32_16x16x32_bf16 v[44:47], v[172:175], v[204:207], v[44:47]
	v_mfma_f32_16x16x32_bf16 v[44:47], v[176:179], v[208:211], v[44:47]
	v_mfma_f32_16x16x32_bf16 v[48:51], v[146:149], v[204:207], v[48:51]
	v_mfma_f32_16x16x32_bf16 v[48:51], v[150:153], v[208:211], v[48:51]
	v_mfma_f32_16x16x32_bf16 v[32:35], v[146:149], v[212:215], v[32:35]
	v_mfma_f32_16x16x32_bf16 v[32:35], v[150:153], v[216:219], v[32:35]
	v_mfma_f32_16x16x32_bf16 v[28:31], v[172:175], v[212:215], v[28:31]
	v_mfma_f32_16x16x32_bf16 v[28:31], v[176:179], v[216:219], v[28:31]
	v_mfma_f32_16x16x32_bf16 v[12:15], v[172:175], v[228:231], v[12:15]
	v_mfma_f32_16x16x32_bf16 v[12:15], v[176:179], v[232:235], v[12:15]
	v_mfma_f32_16x16x32_bf16 v[16:19], v[146:149], v[228:231], v[16:19]
	v_mfma_f32_16x16x32_bf16 v[16:19], v[150:153], v[232:235], v[16:19]
	v_mfma_f32_16x16x32_bf16 v[56:59], v[180:183], v[196:199], v[56:59]
	v_mfma_f32_16x16x32_bf16 v[56:59], v[184:187], v[200:203], v[56:59]
	v_mfma_f32_16x16x32_bf16 v[52:55], v[188:191], v[196:199], v[52:55]
	v_mfma_f32_16x16x32_bf16 v[52:55], v[192:195], v[200:203], v[52:55]
	v_mfma_f32_16x16x32_bf16 v[36:39], v[188:191], v[204:207], v[36:39]
	v_mfma_f32_16x16x32_bf16 v[36:39], v[192:195], v[208:211], v[36:39]
	v_mfma_f32_16x16x32_bf16 v[40:43], v[180:183], v[204:207], v[40:43]
	v_mfma_f32_16x16x32_bf16 v[40:43], v[184:187], v[208:211], v[40:43]
	v_mfma_f32_16x16x32_bf16 v[24:27], v[180:183], v[212:215], v[24:27]
	v_mfma_f32_16x16x32_bf16 v[24:27], v[184:187], v[216:219], v[24:27]
	v_mfma_f32_16x16x32_bf16 v[20:23], v[188:191], v[212:215], v[20:23]
	v_mfma_f32_16x16x32_bf16 v[20:23], v[192:195], v[216:219], v[20:23]
	v_mfma_f32_16x16x32_bf16 v[4:7], v[188:191], v[228:231], v[4:7]
	v_mfma_f32_16x16x32_bf16 v[4:7], v[192:195], v[232:235], v[4:7]
	v_mfma_f32_16x16x32_bf16 v[8:11], v[180:183], v[228:231], v[8:11]
	v_mfma_f32_16x16x32_bf16 v[8:11], v[184:187], v[232:235], v[8:11]
	s_setprio 0
	s_barrier
	s_add_i32 s52, 0, 0x18000
	v_add_u32_e32 v145, s52, v142
	s_add_i32 s53, 0, 0x1c000
	ds_read_b128 v[146:149], v145
	ds_read_b128 v[150:153], v145 offset:1024
	ds_read_b128 v[172:175], v145 offset:2048
	ds_read_b128 v[176:179], v145 offset:3072
	v_add_u32_e32 v145, s53, v142
	ds_read_b128 v[180:183], v145
	ds_read_b128 v[184:187], v145 offset:1024
	ds_read_b128 v[188:191], v145 offset:2048
	ds_read_b128 v[192:195], v145 offset:3072
	s_add_u32 s54, s54, 0x80000
	s_addc_u32 s55, s55, 0
	s_mov_b32 m0, s59
	ds_read_b128 v[196:199], v144 offset:32768
	ds_read_b128 v[200:203], v144 offset:33792
	ds_read_b128 v[204:207], v144 offset:34816
	ds_read_b128 v[208:211], v144 offset:35840
	ds_read_b128 v[212:215], v144 offset:36864
	ds_read_b128 v[216:219], v144 offset:37888
	ds_read_b128 v[228:231], v144 offset:38912
	ds_read_b128 v[232:235], v144 offset:39936
	global_load_lds_dwordx4 v136, s[54:55]
	s_mov_b32 m0, s60
	s_nop 0
	global_load_lds_dwordx4 v132, s[54:55]
	s_waitcnt vmcnt(8)
	s_waitcnt lgkmcnt(0)
	s_barrier
	s_setprio 1
	v_mfma_f32_16x16x32_bf16 v[128:131], v[146:149], v[196:199], v[128:131]
	v_mfma_f32_16x16x32_bf16 v[128:131], v[150:153], v[200:203], v[128:131]
	v_mfma_f32_16x16x32_bf16 v[124:127], v[172:175], v[196:199], v[124:127]
	v_mfma_f32_16x16x32_bf16 v[124:127], v[176:179], v[200:203], v[124:127]
	v_mfma_f32_16x16x32_bf16 v[108:111], v[172:175], v[204:207], v[108:111]
	v_mfma_f32_16x16x32_bf16 v[108:111], v[176:179], v[208:211], v[108:111]
	v_mfma_f32_16x16x32_bf16 v[112:115], v[146:149], v[204:207], v[112:115]
	v_mfma_f32_16x16x32_bf16 v[112:115], v[150:153], v[208:211], v[112:115]
	v_mfma_f32_16x16x32_bf16 v[96:99], v[146:149], v[212:215], v[96:99]
	v_mfma_f32_16x16x32_bf16 v[96:99], v[150:153], v[216:219], v[96:99]
	v_mfma_f32_16x16x32_bf16 v[92:95], v[172:175], v[212:215], v[92:95]
	v_mfma_f32_16x16x32_bf16 v[92:95], v[176:179], v[216:219], v[92:95]
	v_mfma_f32_16x16x32_bf16 v[76:79], v[172:175], v[228:231], v[76:79]
	v_mfma_f32_16x16x32_bf16 v[76:79], v[176:179], v[232:235], v[76:79]
	v_mfma_f32_16x16x32_bf16 v[80:83], v[146:149], v[228:231], v[80:83]
	v_mfma_f32_16x16x32_bf16 v[80:83], v[150:153], v[232:235], v[80:83]
	v_mfma_f32_16x16x32_bf16 v[120:123], v[180:183], v[196:199], v[120:123]
	v_mfma_f32_16x16x32_bf16 v[120:123], v[184:187], v[200:203], v[120:123]
	v_mfma_f32_16x16x32_bf16 v[116:119], v[188:191], v[196:199], v[116:119]
	v_mfma_f32_16x16x32_bf16 v[116:119], v[192:195], v[200:203], v[116:119]
	v_mfma_f32_16x16x32_bf16 v[100:103], v[188:191], v[204:207], v[100:103]
	v_mfma_f32_16x16x32_bf16 v[100:103], v[192:195], v[208:211], v[100:103]
	v_mfma_f32_16x16x32_bf16 v[104:107], v[180:183], v[204:207], v[104:107]
	v_mfma_f32_16x16x32_bf16 v[104:107], v[184:187], v[208:211], v[104:107]
	v_mfma_f32_16x16x32_bf16 v[88:91], v[180:183], v[212:215], v[88:91]
	v_mfma_f32_16x16x32_bf16 v[88:91], v[184:187], v[216:219], v[88:91]
	v_mfma_f32_16x16x32_bf16 v[84:87], v[188:191], v[212:215], v[84:87]
	v_mfma_f32_16x16x32_bf16 v[84:87], v[192:195], v[216:219], v[84:87]
	v_mfma_f32_16x16x32_bf16 v[68:71], v[188:191], v[228:231], v[68:71]
	v_mfma_f32_16x16x32_bf16 v[68:71], v[192:195], v[232:235], v[68:71]
	v_mfma_f32_16x16x32_bf16 v[72:75], v[180:183], v[228:231], v[72:75]
	v_mfma_f32_16x16x32_bf16 v[72:75], v[184:187], v[232:235], v[72:75]
	s_setprio 0
	s_barrier
	s_add_u32 s54, s34, 0x160000
	s_addc_u32 s55, s35, 0
	s_add_i32 s52, s52, s19
	s_mov_b32 m0, s52
	ds_read_b128 v[196:199], v144 offset:49152
	ds_read_b128 v[200:203], v144 offset:50176
	ds_read_b128 v[204:207], v144 offset:51200
	ds_read_b128 v[208:211], v144 offset:52224
	ds_read_b128 v[212:215], v144 offset:53248
	ds_read_b128 v[216:219], v144 offset:54272
	ds_read_b128 v[228:231], v144 offset:55296
	ds_read_b128 v[232:235], v144 offset:56320
	global_load_lds_dwordx4 v134, s[54:55]
	s_add_i32 m0, s52, 0x2000
	s_add_u32 s34, s34, 0x164000
	s_addc_u32 s35, s35, 0
	s_add_i32 s52, s53, s19
	global_load_lds_dwordx4 v0, s[54:55]
	s_mov_b32 m0, s52
	s_nop 0
	global_load_lds_dwordx4 v134, s[34:35]
	s_add_i32 m0, s52, 0x2000
	s_nop 0
	global_load_lds_dwordx4 v0, s[34:35]
	s_mov_b32 m0, s61
	s_nop 0
	global_load_lds_dwordx4 v136, s[100:101]
	s_mov_b32 m0, s62
	s_nop 0
	global_load_lds_dwordx4 v132, s[100:101]
	s_waitcnt vmcnt(8)
	s_waitcnt lgkmcnt(0)
	s_barrier
	s_setprio 1
	v_mfma_f32_16x16x32_bf16 v[64:67], v[146:149], v[196:199], v[64:67]
	v_mfma_f32_16x16x32_bf16 v[64:67], v[150:153], v[200:203], v[64:67]
	v_mfma_f32_16x16x32_bf16 v[60:63], v[172:175], v[196:199], v[60:63]
	v_mfma_f32_16x16x32_bf16 v[60:63], v[176:179], v[200:203], v[60:63]
	v_mfma_f32_16x16x32_bf16 v[44:47], v[172:175], v[204:207], v[44:47]
	v_mfma_f32_16x16x32_bf16 v[44:47], v[176:179], v[208:211], v[44:47]
	v_mfma_f32_16x16x32_bf16 v[48:51], v[146:149], v[204:207], v[48:51]
	v_mfma_f32_16x16x32_bf16 v[48:51], v[150:153], v[208:211], v[48:51]
	v_mfma_f32_16x16x32_bf16 v[32:35], v[146:149], v[212:215], v[32:35]
	v_mfma_f32_16x16x32_bf16 v[32:35], v[150:153], v[216:219], v[32:35]
	v_mfma_f32_16x16x32_bf16 v[28:31], v[172:175], v[212:215], v[28:31]
	v_mfma_f32_16x16x32_bf16 v[28:31], v[176:179], v[216:219], v[28:31]
	v_mfma_f32_16x16x32_bf16 v[12:15], v[172:175], v[228:231], v[12:15]
	v_mfma_f32_16x16x32_bf16 v[12:15], v[176:179], v[232:235], v[12:15]
	v_mfma_f32_16x16x32_bf16 v[16:19], v[146:149], v[228:231], v[16:19]
	v_mfma_f32_16x16x32_bf16 v[16:19], v[150:153], v[232:235], v[16:19]
	v_mfma_f32_16x16x32_bf16 v[56:59], v[180:183], v[196:199], v[56:59]
	v_mfma_f32_16x16x32_bf16 v[56:59], v[184:187], v[200:203], v[56:59]
	v_mfma_f32_16x16x32_bf16 v[52:55], v[188:191], v[196:199], v[52:55]
	v_mfma_f32_16x16x32_bf16 v[52:55], v[192:195], v[200:203], v[52:55]
	v_mfma_f32_16x16x32_bf16 v[36:39], v[188:191], v[204:207], v[36:39]
	v_mfma_f32_16x16x32_bf16 v[36:39], v[192:195], v[208:211], v[36:39]
	v_mfma_f32_16x16x32_bf16 v[40:43], v[180:183], v[204:207], v[40:43]
	v_mfma_f32_16x16x32_bf16 v[40:43], v[184:187], v[208:211], v[40:43]
	v_mfma_f32_16x16x32_bf16 v[24:27], v[180:183], v[212:215], v[24:27]
	v_mfma_f32_16x16x32_bf16 v[24:27], v[184:187], v[216:219], v[24:27]
	v_mfma_f32_16x16x32_bf16 v[20:23], v[188:191], v[212:215], v[20:23]
	v_mfma_f32_16x16x32_bf16 v[20:23], v[192:195], v[216:219], v[20:23]
	v_mfma_f32_16x16x32_bf16 v[4:7], v[188:191], v[228:231], v[4:7]
	v_mfma_f32_16x16x32_bf16 v[4:7], v[192:195], v[232:235], v[4:7]
	v_mfma_f32_16x16x32_bf16 v[8:11], v[180:183], v[228:231], v[8:11]
	v_mfma_f32_16x16x32_bf16 v[8:11], v[184:187], v[232:235], v[8:11]
	s_setprio 0
	s_barrier
	s_add_i32 s77, s77, 2
	s_add_u32 s71, s71, 0x2c0000
	s_addc_u32 s76, s76, 0
	s_add_u32 s50, s50, 0x100
	s_addc_u32 s51, s51, 0
	s_cmp_gt_u32 s77, 29
	s_cbranch_scc0 .LBB0_169
	s_and_b64 vcc, exec, s[28:29]
	s_cbranch_vccz .LBB0_172
	s_barrier

.LBB0_243:
	s_add_u32 s34, s44, 0xfff80080
	s_addc_u32 s35, s45, -1
	s_add_i32 s52, 0, 0x10000
	s_cmp_eq_u32 vcc_hi, 28
	s_cselect_b32 s47, s36, s35
	s_cselect_b32 s46, s37, s34
	s_cselect_b32 s35, s55, vcc_lo
	s_cselect_b32 s34, s57, s63
	s_add_i32 s68, 0, 0x14000
	v_add_u32_e32 v144, s52, v155
	v_add_u32_e32 v180, s68, v155
	ds_read_b128 v[132:135], v144
	ds_read_b128 v[136:139], v144 offset:1024
	ds_read_b128 v[140:143], v144 offset:2048
	ds_read_b128 v[144:147], v144 offset:3072
	ds_read_b128 v[176:179], v180
	ds_read_b128 v[182:185], v180 offset:1024
	ds_read_b128 v[186:189], v180 offset:2048
	ds_read_b128 v[190:193], v180 offset:3072
	s_add_i32 m0, s69, 0xc000
	ds_read_b128 v[194:197], v181
	ds_read_b128 v[198:201], v181 offset:1024
	ds_read_b128 v[202:205], v181 offset:2048
	ds_read_b128 v[206:209], v181 offset:3072
	ds_read_b128 v[210:213], v181 offset:4096
	ds_read_b128 v[214:217], v181 offset:5120
	ds_read_b128 v[228:231], v181 offset:6144
	ds_read_b128 v[232:235], v181 offset:7168
	global_load_lds_dwordx4 v172, s[44:45]
	s_add_i32 m0, s69, 0xe000
	s_nop 0
	global_load_lds_dwordx4 v174, s[44:45]
	s_waitcnt vmcnt(8)
	s_waitcnt lgkmcnt(0)
	s_barrier
	s_setprio 1
	v_mfma_f32_16x16x32_bf16 v[128:131], v[132:135], v[194:197], v[128:131]
	v_mfma_f32_16x16x32_bf16 v[128:131], v[136:139], v[198:201], v[128:131]
	v_mfma_f32_16x16x32_bf16 v[124:127], v[140:143], v[194:197], v[124:127]
	v_mfma_f32_16x16x32_bf16 v[124:127], v[144:147], v[198:201], v[124:127]
	v_mfma_f32_16x16x32_bf16 v[108:111], v[140:143], v[202:205], v[108:111]
	v_mfma_f32_16x16x32_bf16 v[108:111], v[144:147], v[206:209], v[108:111]
	v_mfma_f32_16x16x32_bf16 v[112:115], v[132:135], v[202:205], v[112:115]
	v_mfma_f32_16x16x32_bf16 v[112:115], v[136:139], v[206:209], v[112:115]
	v_mfma_f32_16x16x32_bf16 v[96:99], v[132:135], v[210:213], v[96:99]
	v_mfma_f32_16x16x32_bf16 v[96:99], v[136:139], v[214:217], v[96:99]
	v_mfma_f32_16x16x32_bf16 v[92:95], v[140:143], v[210:213], v[92:95]
	v_mfma_f32_16x16x32_bf16 v[92:95], v[144:147], v[214:217], v[92:95]
	v_mfma_f32_16x16x32_bf16 v[76:79], v[140:143], v[228:231], v[76:79]
	v_mfma_f32_16x16x32_bf16 v[76:79], v[144:147], v[232:235], v[76:79]
	v_mfma_f32_16x16x32_bf16 v[80:83], v[132:135], v[228:231], v[80:83]
	v_mfma_f32_16x16x32_bf16 v[80:83], v[136:139], v[232:235], v[80:83]
	v_mfma_f32_16x16x32_bf16 v[120:123], v[176:179], v[194:197], v[120:123]
	v_mfma_f32_16x16x32_bf16 v[120:123], v[182:185], v[198:201], v[120:123]
	v_mfma_f32_16x16x32_bf16 v[116:119], v[186:189], v[194:197], v[116:119]
	v_mfma_f32_16x16x32_bf16 v[116:119], v[190:193], v[198:201], v[116:119]
	v_mfma_f32_16x16x32_bf16 v[100:103], v[186:189], v[202:205], v[100:103]
	v_mfma_f32_16x16x32_bf16 v[100:103], v[190:193], v[206:209], v[100:103]
	v_mfma_f32_16x16x32_bf16 v[104:107], v[176:179], v[202:205], v[104:107]
	v_mfma_f32_16x16x32_bf16 v[104:107], v[182:185], v[206:209], v[104:107]
	v_mfma_f32_16x16x32_bf16 v[88:91], v[176:179], v[210:213], v[88:91]
	v_mfma_f32_16x16x32_bf16 v[88:91], v[182:185], v[214:217], v[88:91]
	v_mfma_f32_16x16x32_bf16 v[84:87], v[186:189], v[210:213], v[84:87]
	v_mfma_f32_16x16x32_bf16 v[84:87], v[190:193], v[214:217], v[84:87]
	v_mfma_f32_16x16x32_bf16 v[68:71], v[186:189], v[228:231], v[68:71]
	v_mfma_f32_16x16x32_bf16 v[68:71], v[190:193], v[232:235], v[68:71]
	v_mfma_f32_16x16x32_bf16 v[72:75], v[176:179], v[228:231], v[72:75]
	v_mfma_f32_16x16x32_bf16 v[72:75], v[182:185], v[232:235], v[72:75]
	s_setprio 0
	s_barrier
	s_add_u32 s100, s46, s14
	s_addc_u32 s101, s47, s15
	s_add_i32 s52, s52, s2
	s_mov_b32 m0, s52
	ds_read_b128 v[194:197], v181 offset:16384
	ds_read_b128 v[198:201], v181 offset:17408
	ds_read_b128 v[202:205], v181 offset:18432
	ds_read_b128 v[206:209], v181 offset:19456
	ds_read_b128 v[210:213], v181 offset:20480
	ds_read_b128 v[214:217], v181 offset:21504
	ds_read_b128 v[228:231], v181 offset:22528
	ds_read_b128 v[232:235], v181 offset:23552
	global_load_lds_dwordx4 v150, s[34:35]
	s_add_i32 m0, s52, 0x2000
	s_add_u32 s52, s34, 0x4000
	s_addc_u32 s53, s35, 0
	s_add_i32 s68, s68, s2
	global_load_lds_dwordx4 v0, s[34:35]
	s_mov_b32 m0, s68
	s_nop 0
	global_load_lds_dwordx4 v150, s[52:53]
	s_add_i32 m0, s68, 0x2000
	s_nop 0
	global_load_lds_dwordx4 v0, s[52:53]
	s_mov_b32 m0, s69
	s_nop 0
	global_load_lds_dwordx4 v152, s[46:47]
	s_mov_b32 m0, s71
	s_nop 0
	global_load_lds_dwordx4 v148, s[46:47]
	s_waitcnt vmcnt(8)
	s_waitcnt lgkmcnt(0)
	s_barrier
	s_setprio 1
	v_mfma_f32_16x16x32_bf16 v[64:67], v[132:135], v[194:197], v[64:67]
	v_mfma_f32_16x16x32_bf16 v[64:67], v[136:139], v[198:201], v[64:67]
	v_mfma_f32_16x16x32_bf16 v[60:63], v[140:143], v[194:197], v[60:63]
	v_mfma_f32_16x16x32_bf16 v[60:63], v[144:147], v[198:201], v[60:63]
	v_mfma_f32_16x16x32_bf16 v[44:47], v[140:143], v[202:205], v[44:47]
	v_mfma_f32_16x16x32_bf16 v[44:47], v[144:147], v[206:209], v[44:47]
	v_mfma_f32_16x16x32_bf16 v[48:51], v[132:135], v[202:205], v[48:51]
	v_mfma_f32_16x16x32_bf16 v[48:51], v[136:139], v[206:209], v[48:51]
	v_mfma_f32_16x16x32_bf16 v[32:35], v[132:135], v[210:213], v[32:35]
	v_mfma_f32_16x16x32_bf16 v[32:35], v[136:139], v[214:217], v[32:35]
	v_mfma_f32_16x16x32_bf16 v[28:31], v[140:143], v[210:213], v[28:31]
	v_mfma_f32_16x16x32_bf16 v[28:31], v[144:147], v[214:217], v[28:31]
	v_mfma_f32_16x16x32_bf16 v[12:15], v[140:143], v[228:231], v[12:15]
	v_mfma_f32_16x16x32_bf16 v[12:15], v[144:147], v[232:235], v[12:15]
	v_mfma_f32_16x16x32_bf16 v[16:19], v[132:135], v[228:231], v[16:19]
	v_mfma_f32_16x16x32_bf16 v[16:19], v[136:139], v[232:235], v[16:19]
	v_mfma_f32_16x16x32_bf16 v[56:59], v[176:179], v[194:197], v[56:59]
	v_mfma_f32_16x16x32_bf16 v[56:59], v[182:185], v[198:201], v[56:59]
	v_mfma_f32_16x16x32_bf16 v[52:55], v[186:189], v[194:197], v[52:55]
	v_mfma_f32_16x16x32_bf16 v[52:55], v[190:193], v[198:201], v[52:55]
	v_mfma_f32_16x16x32_bf16 v[36:39], v[186:189], v[202:205], v[36:39]
	v_mfma_f32_16x16x32_bf16 v[36:39], v[190:193], v[206:209], v[36:39]
	v_mfma_f32_16x16x32_bf16 v[40:43], v[176:179], v[202:205], v[40:43]
	v_mfma_f32_16x16x32_bf16 v[40:43], v[182:185], v[206:209], v[40:43]
	v_mfma_f32_16x16x32_bf16 v[24:27], v[176:179], v[210:213], v[24:27]
	v_mfma_f32_16x16x32_bf16 v[24:27], v[182:185], v[214:217], v[24:27]
	v_mfma_f32_16x16x32_bf16 v[20:23], v[186:189], v[210:213], v[20:23]
	v_mfma_f32_16x16x32_bf16 v[20:23], v[190:193], v[214:217], v[20:23]
	v_mfma_f32_16x16x32_bf16 v[4:7], v[186:189], v[228:231], v[4:7]
	v_mfma_f32_16x16x32_bf16 v[4:7], v[190:193], v[232:235], v[4:7]
	v_mfma_f32_16x16x32_bf16 v[8:11], v[176:179], v[228:231], v[8:11]
	v_mfma_f32_16x16x32_bf16 v[8:11], v[182:185], v[232:235], v[8:11]
	s_setprio 0
	s_barrier
	s_add_i32 s52, 0, 0x18000
	s_add_i32 s53, 0, 0x1c000
	v_add_u32_e32 v144, s52, v155
	v_add_u32_e32 v180, s53, v155
	ds_read_b128 v[132:135], v144
	ds_read_b128 v[136:139], v144 offset:1024
	ds_read_b128 v[140:143], v144 offset:2048
	ds_read_b128 v[144:147], v144 offset:3072
	ds_read_b128 v[176:179], v180
	ds_read_b128 v[182:185], v180 offset:1024
	ds_read_b128 v[186:189], v180 offset:2048
	ds_read_b128 v[190:193], v180 offset:3072
	s_add_u32 s46, s46, 0x80000
	s_addc_u32 s47, s47, 0
	s_mov_b32 m0, s88
	ds_read_b128 v[194:197], v181 offset:32768
	ds_read_b128 v[198:201], v181 offset:33792
	ds_read_b128 v[202:205], v181 offset:34816
	ds_read_b128 v[206:209], v181 offset:35840
	ds_read_b128 v[210:213], v181 offset:36864
	ds_read_b128 v[214:217], v181 offset:37888
	ds_read_b128 v[228:231], v181 offset:38912
	ds_read_b128 v[232:235], v181 offset:39936
	global_load_lds_dwordx4 v152, s[46:47]
	s_mov_b32 m0, s96
	s_nop 0
	global_load_lds_dwordx4 v148, s[46:47]
	s_waitcnt vmcnt(8)
	s_waitcnt lgkmcnt(0)
	s_barrier
	s_setprio 1
	v_mfma_f32_16x16x32_bf16 v[128:131], v[132:135], v[194:197], v[128:131]
	v_mfma_f32_16x16x32_bf16 v[128:131], v[136:139], v[198:201], v[128:131]
	v_mfma_f32_16x16x32_bf16 v[124:127], v[140:143], v[194:197], v[124:127]
	v_mfma_f32_16x16x32_bf16 v[124:127], v[144:147], v[198:201], v[124:127]
	v_mfma_f32_16x16x32_bf16 v[108:111], v[140:143], v[202:205], v[108:111]
	v_mfma_f32_16x16x32_bf16 v[108:111], v[144:147], v[206:209], v[108:111]
	v_mfma_f32_16x16x32_bf16 v[112:115], v[132:135], v[202:205], v[112:115]
	v_mfma_f32_16x16x32_bf16 v[112:115], v[136:139], v[206:209], v[112:115]
	v_mfma_f32_16x16x32_bf16 v[96:99], v[132:135], v[210:213], v[96:99]
	v_mfma_f32_16x16x32_bf16 v[96:99], v[136:139], v[214:217], v[96:99]
	v_mfma_f32_16x16x32_bf16 v[92:95], v[140:143], v[210:213], v[92:95]
	v_mfma_f32_16x16x32_bf16 v[92:95], v[144:147], v[214:217], v[92:95]
	v_mfma_f32_16x16x32_bf16 v[76:79], v[140:143], v[228:231], v[76:79]
	v_mfma_f32_16x16x32_bf16 v[76:79], v[144:147], v[232:235], v[76:79]
	v_mfma_f32_16x16x32_bf16 v[80:83], v[132:135], v[228:231], v[80:83]
	v_mfma_f32_16x16x32_bf16 v[80:83], v[136:139], v[232:235], v[80:83]
	v_mfma_f32_16x16x32_bf16 v[120:123], v[176:179], v[194:197], v[120:123]
	v_mfma_f32_16x16x32_bf16 v[120:123], v[182:185], v[198:201], v[120:123]
	v_mfma_f32_16x16x32_bf16 v[116:119], v[186:189], v[194:197], v[116:119]
	v_mfma_f32_16x16x32_bf16 v[116:119], v[190:193], v[198:201], v[116:119]
	v_mfma_f32_16x16x32_bf16 v[100:103], v[186:189], v[202:205], v[100:103]
	v_mfma_f32_16x16x32_bf16 v[100:103], v[190:193], v[206:209], v[100:103]
	v_mfma_f32_16x16x32_bf16 v[104:107], v[176:179], v[202:205], v[104:107]
	v_mfma_f32_16x16x32_bf16 v[104:107], v[182:185], v[206:209], v[104:107]
	v_mfma_f32_16x16x32_bf16 v[88:91], v[176:179], v[210:213], v[88:91]
	v_mfma_f32_16x16x32_bf16 v[88:91], v[182:185], v[214:217], v[88:91]
	v_mfma_f32_16x16x32_bf16 v[84:87], v[186:189], v[210:213], v[84:87]
	v_mfma_f32_16x16x32_bf16 v[84:87], v[190:193], v[214:217], v[84:87]
	v_mfma_f32_16x16x32_bf16 v[68:71], v[186:189], v[228:231], v[68:71]
	v_mfma_f32_16x16x32_bf16 v[68:71], v[190:193], v[232:235], v[68:71]
	v_mfma_f32_16x16x32_bf16 v[72:75], v[176:179], v[228:231], v[72:75]
	v_mfma_f32_16x16x32_bf16 v[72:75], v[182:185], v[232:235], v[72:75]
	s_setprio 0
	s_barrier
	s_add_u32 s46, s34, 0x70000
	s_addc_u32 s47, s35, 0
	s_add_i32 s52, s52, s2
	s_mov_b32 m0, s52
	ds_read_b128 v[194:197], v181 offset:49152
	ds_read_b128 v[198:201], v181 offset:50176
	ds_read_b128 v[202:205], v181 offset:51200
	ds_read_b128 v[206:209], v181 offset:52224
	ds_read_b128 v[210:213], v181 offset:53248
	ds_read_b128 v[214:217], v181 offset:54272
	ds_read_b128 v[228:231], v181 offset:55296
	ds_read_b128 v[232:235], v181 offset:56320
	global_load_lds_dwordx4 v150, s[46:47]
	s_add_i32 m0, s52, 0x2000
	s_add_u32 s34, s34, 0x74000
	global_load_lds_dwordx4 v0, s[46:47]
	s_addc_u32 s35, s35, 0
	s_add_i32 s46, s53, s2
	s_mov_b32 m0, s46
	s_nop 0
	global_load_lds_dwordx4 v150, s[34:35]
	s_add_i32 m0, s46, 0x2000
	s_nop 0
	global_load_lds_dwordx4 v0, s[34:35]
	s_mov_b32 m0, s97
	s_nop 0
	global_load_lds_dwordx4 v152, s[100:101]
	s_mov_b32 m0, s76
	s_nop 0
	global_load_lds_dwordx4 v148, s[100:101]
	s_waitcnt vmcnt(8)
	s_waitcnt lgkmcnt(0)
	s_barrier
	s_setprio 1
	v_mfma_f32_16x16x32_bf16 v[64:67], v[132:135], v[194:197], v[64:67]
	v_mfma_f32_16x16x32_bf16 v[64:67], v[136:139], v[198:201], v[64:67]
	v_mfma_f32_16x16x32_bf16 v[60:63], v[140:143], v[194:197], v[60:63]
	v_mfma_f32_16x16x32_bf16 v[60:63], v[144:147], v[198:201], v[60:63]
	v_mfma_f32_16x16x32_bf16 v[44:47], v[140:143], v[202:205], v[44:47]
	v_mfma_f32_16x16x32_bf16 v[44:47], v[144:147], v[206:209], v[44:47]
	v_mfma_f32_16x16x32_bf16 v[48:51], v[132:135], v[202:205], v[48:51]
	v_mfma_f32_16x16x32_bf16 v[48:51], v[136:139], v[206:209], v[48:51]
	v_mfma_f32_16x16x32_bf16 v[32:35], v[132:135], v[210:213], v[32:35]
	v_mfma_f32_16x16x32_bf16 v[32:35], v[136:139], v[214:217], v[32:35]
	v_mfma_f32_16x16x32_bf16 v[28:31], v[140:143], v[210:213], v[28:31]
	v_mfma_f32_16x16x32_bf16 v[28:31], v[144:147], v[214:217], v[28:31]
	v_mfma_f32_16x16x32_bf16 v[12:15], v[140:143], v[228:231], v[12:15]
	v_mfma_f32_16x16x32_bf16 v[12:15], v[144:147], v[232:235], v[12:15]
	v_mfma_f32_16x16x32_bf16 v[16:19], v[132:135], v[228:231], v[16:19]
	v_mfma_f32_16x16x32_bf16 v[16:19], v[136:139], v[232:235], v[16:19]
	v_mfma_f32_16x16x32_bf16 v[56:59], v[176:179], v[194:197], v[56:59]
	v_mfma_f32_16x16x32_bf16 v[56:59], v[182:185], v[198:201], v[56:59]
	v_mfma_f32_16x16x32_bf16 v[52:55], v[186:189], v[194:197], v[52:55]
	v_mfma_f32_16x16x32_bf16 v[52:55], v[190:193], v[198:201], v[52:55]
	v_mfma_f32_16x16x32_bf16 v[36:39], v[186:189], v[202:205], v[36:39]
	v_mfma_f32_16x16x32_bf16 v[36:39], v[190:193], v[206:209], v[36:39]
	v_mfma_f32_16x16x32_bf16 v[40:43], v[176:179], v[202:205], v[40:43]
	v_mfma_f32_16x16x32_bf16 v[40:43], v[182:185], v[206:209], v[40:43]
	v_mfma_f32_16x16x32_bf16 v[24:27], v[176:179], v[210:213], v[24:27]
	v_mfma_f32_16x16x32_bf16 v[24:27], v[182:185], v[214:217], v[24:27]
	v_mfma_f32_16x16x32_bf16 v[20:23], v[186:189], v[210:213], v[20:23]
	v_mfma_f32_16x16x32_bf16 v[20:23], v[190:193], v[214:217], v[20:23]
	v_mfma_f32_16x16x32_bf16 v[4:7], v[186:189], v[228:231], v[4:7]
	v_mfma_f32_16x16x32_bf16 v[4:7], v[190:193], v[232:235], v[4:7]
	v_mfma_f32_16x16x32_bf16 v[8:11], v[176:179], v[228:231], v[8:11]
	v_mfma_f32_16x16x32_bf16 v[8:11], v[182:185], v[232:235], v[8:11]
	s_setprio 0
	s_barrier
	s_add_i32 vcc_hi, vcc_hi, 2
	s_add_u32 s63, s63, 0xe0000
	s_addc_u32 vcc_lo, vcc_lo, 0
	s_add_u32 s44, s44, 0x100
	s_addc_u32 s45, s45, 0
	s_cmp_gt_u32 vcc_hi, 29
	s_cbranch_scc0 .LBB0_243
	s_and_b64 vcc, exec, s[28:29]
	s_cbranch_vccz .LBB0_246
	s_barrier

.LBB0_559:
	s_add_i32 vcc_lo, s34, 2
	s_add_u32 s35, s42, 0x80
	s_addc_u32 s52, s43, 0
	s_add_i32 s53, 0, 0x10000
	s_cmp_eq_u32 s77, s34
	s_cselect_b32 s57, s51, s52
	s_cselect_b32 s56, s50, s35
	s_cselect_b32 s35, s36, s97
	s_cselect_b32 s34, s37, s49
	s_add_i32 s68, 0, 0x14000
	v_add_u32_e32 v136, s53, v200
	v_add_u32_e32 v186, s68, v200
	ds_read_b128 v[116:119], v136
	ds_read_b128 v[120:123], v136 offset:1024
	ds_read_b128 v[124:127], v136 offset:2048
	ds_read_b128 v[136:139], v136 offset:3072
	ds_read_b128 v[148:151], v186
	ds_read_b128 v[152:155], v186 offset:1024
	ds_read_b128 v[182:185], v186 offset:2048
	ds_read_b128 v[186:189], v186 offset:3072
	s_add_i32 m0, s59, 0xc000
	ds_read_b128 v[190:193], v202
	ds_read_b128 v[194:197], v202 offset:1024
	ds_read_b128 v[204:207], v202 offset:2048
	ds_read_b128 v[208:211], v202 offset:3072
	ds_read_b128 v[212:215], v202 offset:4096
	ds_read_b128 v[216:219], v202 offset:5120
	ds_read_b128 v[228:231], v202 offset:6144
	ds_read_b128 v[232:235], v202 offset:7168
	global_load_lds_dwordx4 v178, s[42:43]
	s_add_i32 m0, s59, 0xe000
	s_nop 0
	global_load_lds_dwordx4 v180, s[42:43]
	s_waitcnt vmcnt(8)
	s_waitcnt lgkmcnt(0)
	s_barrier
	s_setprio 1
	v_mfma_f32_16x16x32_bf16 v[144:147], v[116:119], v[190:193], v[144:147]
	v_mfma_f32_16x16x32_bf16 v[144:147], v[120:123], v[194:197], v[144:147]
	v_mfma_f32_16x16x32_bf16 v[140:143], v[124:127], v[190:193], v[140:143]
	v_mfma_f32_16x16x32_bf16 v[140:143], v[136:139], v[194:197], v[140:143]
	v_mfma_f32_16x16x32_bf16 v[108:111], v[124:127], v[204:207], v[108:111]
	v_mfma_f32_16x16x32_bf16 v[108:111], v[136:139], v[208:211], v[108:111]
	v_mfma_f32_16x16x32_bf16 v[112:115], v[116:119], v[204:207], v[112:115]
	v_mfma_f32_16x16x32_bf16 v[112:115], v[120:123], v[208:211], v[112:115]
	v_mfma_f32_16x16x32_bf16 v[96:99], v[116:119], v[212:215], v[96:99]
	v_mfma_f32_16x16x32_bf16 v[96:99], v[120:123], v[216:219], v[96:99]
	v_mfma_f32_16x16x32_bf16 v[92:95], v[124:127], v[212:215], v[92:95]
	v_mfma_f32_16x16x32_bf16 v[92:95], v[136:139], v[216:219], v[92:95]
	v_mfma_f32_16x16x32_bf16 v[76:79], v[124:127], v[228:231], v[76:79]
	v_mfma_f32_16x16x32_bf16 v[76:79], v[136:139], v[232:235], v[76:79]
	v_mfma_f32_16x16x32_bf16 v[80:83], v[116:119], v[228:231], v[80:83]
	v_mfma_f32_16x16x32_bf16 v[80:83], v[120:123], v[232:235], v[80:83]
	v_mfma_f32_16x16x32_bf16 v[132:135], v[148:151], v[190:193], v[132:135]
	v_mfma_f32_16x16x32_bf16 v[132:135], v[152:155], v[194:197], v[132:135]
	v_mfma_f32_16x16x32_bf16 v[128:131], v[182:185], v[190:193], v[128:131]
	v_mfma_f32_16x16x32_bf16 v[128:131], v[186:189], v[194:197], v[128:131]
	v_mfma_f32_16x16x32_bf16 v[100:103], v[182:185], v[204:207], v[100:103]
	v_mfma_f32_16x16x32_bf16 v[100:103], v[186:189], v[208:211], v[100:103]
	v_mfma_f32_16x16x32_bf16 v[104:107], v[148:151], v[204:207], v[104:107]
	v_mfma_f32_16x16x32_bf16 v[104:107], v[152:155], v[208:211], v[104:107]
	v_mfma_f32_16x16x32_bf16 v[88:91], v[148:151], v[212:215], v[88:91]
	v_mfma_f32_16x16x32_bf16 v[88:91], v[152:155], v[216:219], v[88:91]
	v_mfma_f32_16x16x32_bf16 v[84:87], v[182:185], v[212:215], v[84:87]
	v_mfma_f32_16x16x32_bf16 v[84:87], v[186:189], v[216:219], v[84:87]
	v_mfma_f32_16x16x32_bf16 v[68:71], v[182:185], v[228:231], v[68:71]
	v_mfma_f32_16x16x32_bf16 v[68:71], v[186:189], v[232:235], v[68:71]
	v_mfma_f32_16x16x32_bf16 v[72:75], v[148:151], v[228:231], v[72:75]
	v_mfma_f32_16x16x32_bf16 v[72:75], v[152:155], v[232:235], v[72:75]
	s_setprio 0
	s_barrier
	s_add_u32 s100, s56, s14
	s_addc_u32 s101, s57, s15
	s_add_i32 s52, s53, s58
	s_mov_b32 m0, s52
	ds_read_b128 v[190:193], v202 offset:16384
	ds_read_b128 v[194:197], v202 offset:17408
	ds_read_b128 v[204:207], v202 offset:18432
	ds_read_b128 v[208:211], v202 offset:19456
	ds_read_b128 v[212:215], v202 offset:20480
	ds_read_b128 v[216:219], v202 offset:21504
	ds_read_b128 v[228:231], v202 offset:22528
	ds_read_b128 v[232:235], v202 offset:23552
	global_load_lds_dwordx4 v174, s[34:35]
	s_add_i32 m0, s52, 0x2000
	s_add_u32 s52, s34, 0x4000
	s_addc_u32 s53, s35, 0
	s_add_i32 s68, s68, s58
	global_load_lds_dwordx4 v0, s[34:35]
	s_mov_b32 m0, s68
	s_nop 0
	global_load_lds_dwordx4 v174, s[52:53]
	s_add_i32 m0, s68, 0x2000
	s_nop 0
	global_load_lds_dwordx4 v0, s[52:53]
	s_mov_b32 m0, s59
	s_nop 0
	global_load_lds_dwordx4 v176, s[56:57]
	s_mov_b32 m0, s60
	s_nop 0
	global_load_lds_dwordx4 v172, s[56:57]
	s_waitcnt vmcnt(8)
	s_waitcnt lgkmcnt(0)
	s_barrier
	s_setprio 1
	v_mfma_f32_16x16x32_bf16 v[64:67], v[116:119], v[190:193], v[64:67]
	v_mfma_f32_16x16x32_bf16 v[64:67], v[120:123], v[194:197], v[64:67]
	v_mfma_f32_16x16x32_bf16 v[60:63], v[124:127], v[190:193], v[60:63]
	v_mfma_f32_16x16x32_bf16 v[60:63], v[136:139], v[194:197], v[60:63]
	v_mfma_f32_16x16x32_bf16 v[44:47], v[124:127], v[204:207], v[44:47]
	v_mfma_f32_16x16x32_bf16 v[44:47], v[136:139], v[208:211], v[44:47]
	v_mfma_f32_16x16x32_bf16 v[48:51], v[116:119], v[204:207], v[48:51]
	v_mfma_f32_16x16x32_bf16 v[48:51], v[120:123], v[208:211], v[48:51]
	v_mfma_f32_16x16x32_bf16 v[32:35], v[116:119], v[212:215], v[32:35]
	v_mfma_f32_16x16x32_bf16 v[32:35], v[120:123], v[216:219], v[32:35]
	v_mfma_f32_16x16x32_bf16 v[28:31], v[124:127], v[212:215], v[28:31]
	v_mfma_f32_16x16x32_bf16 v[28:31], v[136:139], v[216:219], v[28:31]
	v_mfma_f32_16x16x32_bf16 v[12:15], v[124:127], v[228:231], v[12:15]
	v_mfma_f32_16x16x32_bf16 v[12:15], v[136:139], v[232:235], v[12:15]
	v_mfma_f32_16x16x32_bf16 v[16:19], v[116:119], v[228:231], v[16:19]
	v_mfma_f32_16x16x32_bf16 v[16:19], v[120:123], v[232:235], v[16:19]
	v_mfma_f32_16x16x32_bf16 v[56:59], v[148:151], v[190:193], v[56:59]
	v_mfma_f32_16x16x32_bf16 v[56:59], v[152:155], v[194:197], v[56:59]
	v_mfma_f32_16x16x32_bf16 v[52:55], v[182:185], v[190:193], v[52:55]
	v_mfma_f32_16x16x32_bf16 v[52:55], v[186:189], v[194:197], v[52:55]
	v_mfma_f32_16x16x32_bf16 v[36:39], v[182:185], v[204:207], v[36:39]
	v_mfma_f32_16x16x32_bf16 v[36:39], v[186:189], v[208:211], v[36:39]
	v_mfma_f32_16x16x32_bf16 v[40:43], v[148:151], v[204:207], v[40:43]
	v_mfma_f32_16x16x32_bf16 v[40:43], v[152:155], v[208:211], v[40:43]
	v_mfma_f32_16x16x32_bf16 v[24:27], v[148:151], v[212:215], v[24:27]
	v_mfma_f32_16x16x32_bf16 v[24:27], v[152:155], v[216:219], v[24:27]
	v_mfma_f32_16x16x32_bf16 v[20:23], v[182:185], v[212:215], v[20:23]
	v_mfma_f32_16x16x32_bf16 v[20:23], v[186:189], v[216:219], v[20:23]
	v_mfma_f32_16x16x32_bf16 v[4:7], v[182:185], v[228:231], v[4:7]
	v_mfma_f32_16x16x32_bf16 v[4:7], v[186:189], v[232:235], v[4:7]
	v_mfma_f32_16x16x32_bf16 v[8:11], v[148:151], v[228:231], v[8:11]
	v_mfma_f32_16x16x32_bf16 v[8:11], v[152:155], v[232:235], v[8:11]
	s_setprio 0
	s_barrier
	s_add_i32 s68, 0, 0x18000
	s_add_i32 vcc_hi, 0, 0x1c000
	v_add_u32_e32 v136, s68, v200
	v_add_u32_e32 v186, vcc_hi, v200
	ds_read_b128 v[116:119], v136
	ds_read_b128 v[120:123], v136 offset:1024
	ds_read_b128 v[124:127], v136 offset:2048
	ds_read_b128 v[136:139], v136 offset:3072
	ds_read_b128 v[148:151], v186
	ds_read_b128 v[152:155], v186 offset:1024
	ds_read_b128 v[182:185], v186 offset:2048
	ds_read_b128 v[186:189], v186 offset:3072
	s_add_u32 s52, s56, s26
	s_addc_u32 s53, s57, 0
	s_mov_b32 m0, s61
	ds_read_b128 v[190:193], v202 offset:32768
	ds_read_b128 v[194:197], v202 offset:33792
	ds_read_b128 v[204:207], v202 offset:34816
	ds_read_b128 v[208:211], v202 offset:35840
	ds_read_b128 v[212:215], v202 offset:36864
	ds_read_b128 v[216:219], v202 offset:37888
	ds_read_b128 v[228:231], v202 offset:38912
	ds_read_b128 v[232:235], v202 offset:39936
	global_load_lds_dwordx4 v176, s[52:53]
	s_mov_b32 m0, s62
	s_nop 0
	global_load_lds_dwordx4 v172, s[52:53]
	s_waitcnt vmcnt(8)
	s_waitcnt lgkmcnt(0)
	s_barrier
	s_setprio 1
	v_mfma_f32_16x16x32_bf16 v[144:147], v[116:119], v[190:193], v[144:147]
	v_mfma_f32_16x16x32_bf16 v[144:147], v[120:123], v[194:197], v[144:147]
	v_mfma_f32_16x16x32_bf16 v[140:143], v[124:127], v[190:193], v[140:143]
	v_mfma_f32_16x16x32_bf16 v[140:143], v[136:139], v[194:197], v[140:143]
	v_mfma_f32_16x16x32_bf16 v[108:111], v[124:127], v[204:207], v[108:111]
	v_mfma_f32_16x16x32_bf16 v[108:111], v[136:139], v[208:211], v[108:111]
	v_mfma_f32_16x16x32_bf16 v[112:115], v[116:119], v[204:207], v[112:115]
	v_mfma_f32_16x16x32_bf16 v[112:115], v[120:123], v[208:211], v[112:115]
	v_mfma_f32_16x16x32_bf16 v[96:99], v[116:119], v[212:215], v[96:99]
	v_mfma_f32_16x16x32_bf16 v[96:99], v[120:123], v[216:219], v[96:99]
	v_mfma_f32_16x16x32_bf16 v[92:95], v[124:127], v[212:215], v[92:95]
	v_mfma_f32_16x16x32_bf16 v[92:95], v[136:139], v[216:219], v[92:95]
	v_mfma_f32_16x16x32_bf16 v[76:79], v[124:127], v[228:231], v[76:79]
	v_mfma_f32_16x16x32_bf16 v[76:79], v[136:139], v[232:235], v[76:79]
	v_mfma_f32_16x16x32_bf16 v[80:83], v[116:119], v[228:231], v[80:83]
	v_mfma_f32_16x16x32_bf16 v[80:83], v[120:123], v[232:235], v[80:83]
	v_mfma_f32_16x16x32_bf16 v[132:135], v[148:151], v[190:193], v[132:135]
	v_mfma_f32_16x16x32_bf16 v[132:135], v[152:155], v[194:197], v[132:135]
	v_mfma_f32_16x16x32_bf16 v[128:131], v[182:185], v[190:193], v[128:131]
	v_mfma_f32_16x16x32_bf16 v[128:131], v[186:189], v[194:197], v[128:131]
	v_mfma_f32_16x16x32_bf16 v[100:103], v[182:185], v[204:207], v[100:103]
	v_mfma_f32_16x16x32_bf16 v[100:103], v[186:189], v[208:211], v[100:103]
	v_mfma_f32_16x16x32_bf16 v[104:107], v[148:151], v[204:207], v[104:107]
	v_mfma_f32_16x16x32_bf16 v[104:107], v[152:155], v[208:211], v[104:107]
	v_mfma_f32_16x16x32_bf16 v[88:91], v[148:151], v[212:215], v[88:91]
	v_mfma_f32_16x16x32_bf16 v[88:91], v[152:155], v[216:219], v[88:91]
	v_mfma_f32_16x16x32_bf16 v[84:87], v[182:185], v[212:215], v[84:87]
	v_mfma_f32_16x16x32_bf16 v[84:87], v[186:189], v[216:219], v[84:87]
	v_mfma_f32_16x16x32_bf16 v[68:71], v[182:185], v[228:231], v[68:71]
	v_mfma_f32_16x16x32_bf16 v[68:71], v[186:189], v[232:235], v[68:71]
	v_mfma_f32_16x16x32_bf16 v[72:75], v[148:151], v[228:231], v[72:75]
	v_mfma_f32_16x16x32_bf16 v[72:75], v[152:155], v[232:235], v[72:75]
	s_setprio 0
	s_barrier
	s_add_u32 s52, s34, 0x40000
	s_addc_u32 s53, s35, 0
	s_add_i32 s56, s68, s58
	s_mov_b32 m0, s56
	ds_read_b128 v[190:193], v202 offset:49152
	ds_read_b128 v[194:197], v202 offset:50176
	ds_read_b128 v[204:207], v202 offset:51200
	ds_read_b128 v[208:211], v202 offset:52224
	ds_read_b128 v[212:215], v202 offset:53248
	ds_read_b128 v[216:219], v202 offset:54272
	ds_read_b128 v[228:231], v202 offset:55296
	ds_read_b128 v[232:235], v202 offset:56320
	global_load_lds_dwordx4 v174, s[52:53]
	s_add_i32 m0, s56, 0x2000
	s_add_u32 s34, s34, 0x44000
	global_load_lds_dwordx4 v0, s[52:53]
	s_addc_u32 s35, s35, 0
	s_add_i32 s52, vcc_hi, s58
	s_mov_b32 m0, s52
	s_nop 0
	global_load_lds_dwordx4 v174, s[34:35]
	s_add_i32 m0, s52, 0x2000
	s_nop 0
	global_load_lds_dwordx4 v0, s[34:35]
	s_mov_b32 m0, s71
	s_nop 0
	global_load_lds_dwordx4 v176, s[100:101]
	s_mov_b32 m0, s76
	s_nop 0
	global_load_lds_dwordx4 v172, s[100:101]
	s_waitcnt vmcnt(8)
	s_waitcnt lgkmcnt(0)
	s_barrier
	s_setprio 1
	v_mfma_f32_16x16x32_bf16 v[64:67], v[116:119], v[190:193], v[64:67]
	v_mfma_f32_16x16x32_bf16 v[64:67], v[120:123], v[194:197], v[64:67]
	v_mfma_f32_16x16x32_bf16 v[60:63], v[124:127], v[190:193], v[60:63]
	v_mfma_f32_16x16x32_bf16 v[60:63], v[136:139], v[194:197], v[60:63]
	v_mfma_f32_16x16x32_bf16 v[44:47], v[124:127], v[204:207], v[44:47]
	v_mfma_f32_16x16x32_bf16 v[44:47], v[136:139], v[208:211], v[44:47]
	v_mfma_f32_16x16x32_bf16 v[48:51], v[116:119], v[204:207], v[48:51]
	v_mfma_f32_16x16x32_bf16 v[48:51], v[120:123], v[208:211], v[48:51]
	v_mfma_f32_16x16x32_bf16 v[32:35], v[116:119], v[212:215], v[32:35]
	v_mfma_f32_16x16x32_bf16 v[32:35], v[120:123], v[216:219], v[32:35]
	v_mfma_f32_16x16x32_bf16 v[28:31], v[124:127], v[212:215], v[28:31]
	v_mfma_f32_16x16x32_bf16 v[28:31], v[136:139], v[216:219], v[28:31]
	v_mfma_f32_16x16x32_bf16 v[12:15], v[124:127], v[228:231], v[12:15]
	v_mfma_f32_16x16x32_bf16 v[12:15], v[136:139], v[232:235], v[12:15]
	v_mfma_f32_16x16x32_bf16 v[16:19], v[116:119], v[228:231], v[16:19]
	v_mfma_f32_16x16x32_bf16 v[16:19], v[120:123], v[232:235], v[16:19]
	v_mfma_f32_16x16x32_bf16 v[56:59], v[148:151], v[190:193], v[56:59]
	v_mfma_f32_16x16x32_bf16 v[56:59], v[152:155], v[194:197], v[56:59]
	v_mfma_f32_16x16x32_bf16 v[52:55], v[182:185], v[190:193], v[52:55]
	v_mfma_f32_16x16x32_bf16 v[52:55], v[186:189], v[194:197], v[52:55]
	v_mfma_f32_16x16x32_bf16 v[36:39], v[182:185], v[204:207], v[36:39]
	v_mfma_f32_16x16x32_bf16 v[36:39], v[186:189], v[208:211], v[36:39]
	v_mfma_f32_16x16x32_bf16 v[40:43], v[148:151], v[204:207], v[40:43]
	v_mfma_f32_16x16x32_bf16 v[40:43], v[152:155], v[208:211], v[40:43]
	v_mfma_f32_16x16x32_bf16 v[24:27], v[148:151], v[212:215], v[24:27]
	v_mfma_f32_16x16x32_bf16 v[24:27], v[152:155], v[216:219], v[24:27]
	v_mfma_f32_16x16x32_bf16 v[20:23], v[182:185], v[212:215], v[20:23]
	v_mfma_f32_16x16x32_bf16 v[20:23], v[186:189], v[216:219], v[20:23]
	v_mfma_f32_16x16x32_bf16 v[4:7], v[182:185], v[228:231], v[4:7]
	v_mfma_f32_16x16x32_bf16 v[4:7], v[186:189], v[232:235], v[4:7]
	v_mfma_f32_16x16x32_bf16 v[8:11], v[148:151], v[228:231], v[8:11]
	v_mfma_f32_16x16x32_bf16 v[8:11], v[152:155], v[232:235], v[8:11]
	s_setprio 0
	s_barrier
	s_add_u32 s49, s49, 0x80000
	s_addc_u32 s97, s97, 0
	s_add_u32 s42, s42, 0x100
	s_addc_u32 s43, s43, 0
	s_cmp_ge_u32 vcc_lo, s69
	s_mov_b32 s34, vcc_lo
	s_cbranch_scc0 .LBB0_559
	s_and_b64 vcc, exec, s[46:47]
	s_cbranch_vccz .LBB0_562
	s_barrier
